# E11 + GEMM accumulator zeroing between units with 64 v_mov_b64 instead of 128 v_mov_b32 (all 12 GEMM instances)
# speedup vs baseline: 1.0299x; 1.0087x over previous
; template <class Epi, class Sched, bool ALIGN_EPI = false, bool SP2 = false>
; __device__ __forceinline__ void gemm_phase(PG8_LAS unsigned char* lds, const Gemm g, const Sched& S, const Epi& E) {
;     ...
;         const bool has_next = S.next(ui + 1, nxt);
;         const char* nA = has_next ? (const char*)g.A + (size_t)nxt.pm * tstep : cA; const char* nB = has_next ? (const char*)g.Bt + (size_t)nxt.pn * tstep : cB;
;         for (int t = 0; t < nt; t += 2) {
;             const bool last = (t == nt - 2);
;             const char* a1 = cA + (size_t)(t + 1) * kstep;
;             const char* a2 = last ? nA : cA + (size_t)(t + 2) * kstep; const char* b2 = last ? nB : cB + (size_t)(t + 2) * kstep;
;             const char* a3 = a2 + kstep; const char* b3 = b2 + kstep;
;     ...
;         for (int a = 0; a < 2; ++a)
; #pragma unroll
;             for (int b = 0; b < 2; ++b)
; #pragma unroll
;                 for (int m = 0; m < 4; ++m)
; #pragma unroll
;                     for (int n = 0; n < 2; ++n) acc[a][b][m][n] = (f32x4){0.f, 0.f, 0.f, 0.f};
;         cur = nxt; cA = nA; cB = nB; ++ui;
.LBB0_123:
	s_ashr_i32 s13, s12, 31
	s_lshl_b64 s[14:15], s[12:13], 19
	s_add_u32 s14, s29, s14
	s_addc_u32 s15, s30, s15
	s_and_b64 s[16:17], s[2:3], exec
	s_cselect_b32 s13, s15, s23
	s_cselect_b32 s45, s14, s22
	s_ashr_i32 s11, s10, 31
	s_lshl_b64 s[16:17], s[10:11], 19
	s_add_u32 s16, s27, s16
	s_addc_u32 s17, s26, s17
	s_and_b64 s[24:25], s[2:3], exec
	s_cselect_b32 s11, s17, s21
	s_cselect_b32 s46, s16, s20
	s_add_u32 s47, s20, 0x100
	s_addc_u32 s48, s21, 0
	s_add_u32 s20, s22, 0x40080
	v_mov_b64_e32 v[0:1], 0
	s_addc_u32 s21, s23, 0
	s_mov_b32 s49, -2
	v_mov_b64_e32 v[2:3], 0
	v_mov_b64_e32 v[4:5], 0
	v_mov_b64_e32 v[6:7], 0
	v_mov_b64_e32 v[8:9], 0
	v_mov_b64_e32 v[10:11], 0
	v_mov_b64_e32 v[12:13], 0
	v_mov_b64_e32 v[14:15], 0
	v_mov_b64_e32 v[16:17], 0
	v_mov_b64_e32 v[18:19], 0
	v_mov_b64_e32 v[20:21], 0
	v_mov_b64_e32 v[22:23], 0
	v_mov_b64_e32 v[24:25], 0
	v_mov_b64_e32 v[26:27], 0
	v_mov_b64_e32 v[28:29], 0
	v_mov_b64_e32 v[30:31], 0
	v_mov_b64_e32 v[32:33], 0
	v_mov_b64_e32 v[34:35], 0
	v_mov_b64_e32 v[36:37], 0
	v_mov_b64_e32 v[38:39], 0
	v_mov_b64_e32 v[40:41], 0
	v_mov_b64_e32 v[42:43], 0
	v_mov_b64_e32 v[44:45], 0
	v_mov_b64_e32 v[46:47], 0
	v_mov_b64_e32 v[48:49], 0
	v_mov_b64_e32 v[50:51], 0
	v_mov_b64_e32 v[52:53], 0
	v_mov_b64_e32 v[54:55], 0
	v_mov_b64_e32 v[56:57], 0
	v_mov_b64_e32 v[58:59], 0
	v_mov_b64_e32 v[60:61], 0
	v_mov_b64_e32 v[62:63], 0
	v_mov_b64_e32 v[64:65], 0
	v_mov_b64_e32 v[66:67], 0
	v_mov_b64_e32 v[68:69], 0
	v_mov_b64_e32 v[70:71], 0
	v_mov_b64_e32 v[72:73], 0
	v_mov_b64_e32 v[74:75], 0
	v_mov_b64_e32 v[76:77], 0
	v_mov_b64_e32 v[78:79], 0
	v_mov_b64_e32 v[80:81], 0
	v_mov_b64_e32 v[82:83], 0
	v_mov_b64_e32 v[84:85], 0
	v_mov_b64_e32 v[86:87], 0
	v_mov_b64_e32 v[88:89], 0
	v_mov_b64_e32 v[90:91], 0
	v_mov_b64_e32 v[92:93], 0
	v_mov_b64_e32 v[94:95], 0
	v_mov_b64_e32 v[96:97], 0
	v_mov_b64_e32 v[98:99], 0
	v_mov_b64_e32 v[100:101], 0
	v_mov_b64_e32 v[102:103], 0
	v_mov_b64_e32 v[104:105], 0
	v_mov_b64_e32 v[106:107], 0
	v_mov_b64_e32 v[108:109], 0
	v_mov_b64_e32 v[110:111], 0
	v_mov_b64_e32 v[112:113], 0
	v_mov_b64_e32 v[114:115], 0
	v_mov_b64_e32 v[116:117], 0
	v_mov_b64_e32 v[118:119], 0
	v_mov_b64_e32 v[120:121], 0
	v_mov_b64_e32 v[122:123], 0
	v_mov_b64_e32 v[124:125], 0
	v_mov_b64_e32 v[126:127], 0

; template <class Epi, class Sched, bool ALIGN_EPI = false, bool SP2 = false>
; __device__ __forceinline__ void gemm_phase(PG8_LAS unsigned char* lds, const Gemm g, const Sched& S, const Epi& E) {
;     ...
;         const bool has_next = S.next(ui + 1, nxt);
;         const char* nA = has_next ? (const char*)g.A + (size_t)nxt.pm * tstep : cA; const char* nB = has_next ? (const char*)g.Bt + (size_t)nxt.pn * tstep : cB;
;         for (int t = 0; t < nt; t += 2) {
;             const bool last = (t == nt - 2);
;             const char* a1 = cA + (size_t)(t + 1) * kstep;
;             const char* a2 = last ? nA : cA + (size_t)(t + 2) * kstep; const char* b2 = last ? nB : cB + (size_t)(t + 2) * kstep;
;             const char* a3 = a2 + kstep; const char* b3 = b2 + kstep;
;     ...
;         for (int a = 0; a < 2; ++a)
; #pragma unroll
;             for (int b = 0; b < 2; ++b)
; #pragma unroll
;                 for (int m = 0; m < 4; ++m)
; #pragma unroll
;                     for (int n = 0; n < 2; ++n) acc[a][b][m][n] = (f32x4){0.f, 0.f, 0.f, 0.f};
;         cur = nxt; cA = nA; cB = nB; ++ui;
.LBB0_195:
	s_add_u32 s56, s24, 0x100
	v_mov_b64_e32 v[0:1], 0
	s_addc_u32 s57, s25, 0
	s_mov_b32 s58, -2
	v_mov_b64_e32 v[2:3], 0
	v_mov_b64_e32 v[4:5], 0
	v_mov_b64_e32 v[6:7], 0
	v_mov_b64_e32 v[8:9], 0
	v_mov_b64_e32 v[10:11], 0
	v_mov_b64_e32 v[12:13], 0
	v_mov_b64_e32 v[14:15], 0
	v_mov_b64_e32 v[16:17], 0
	v_mov_b64_e32 v[18:19], 0
	v_mov_b64_e32 v[20:21], 0
	v_mov_b64_e32 v[22:23], 0
	v_mov_b64_e32 v[24:25], 0
	v_mov_b64_e32 v[26:27], 0
	v_mov_b64_e32 v[28:29], 0
	v_mov_b64_e32 v[30:31], 0
	v_mov_b64_e32 v[32:33], 0
	v_mov_b64_e32 v[34:35], 0
	v_mov_b64_e32 v[36:37], 0
	v_mov_b64_e32 v[38:39], 0
	v_mov_b64_e32 v[40:41], 0
	v_mov_b64_e32 v[42:43], 0
	v_mov_b64_e32 v[44:45], 0
	v_mov_b64_e32 v[46:47], 0
	v_mov_b64_e32 v[48:49], 0
	v_mov_b64_e32 v[50:51], 0
	v_mov_b64_e32 v[52:53], 0
	v_mov_b64_e32 v[54:55], 0
	v_mov_b64_e32 v[56:57], 0
	v_mov_b64_e32 v[58:59], 0
	v_mov_b64_e32 v[60:61], 0
	v_mov_b64_e32 v[62:63], 0
	v_mov_b64_e32 v[64:65], 0
	v_mov_b64_e32 v[66:67], 0
	v_mov_b64_e32 v[68:69], 0
	v_mov_b64_e32 v[70:71], 0
	v_mov_b64_e32 v[72:73], 0
	v_mov_b64_e32 v[74:75], 0
	v_mov_b64_e32 v[76:77], 0
	v_mov_b64_e32 v[78:79], 0
	v_mov_b64_e32 v[80:81], 0
	v_mov_b64_e32 v[82:83], 0
	v_mov_b64_e32 v[84:85], 0
	v_mov_b64_e32 v[86:87], 0
	v_mov_b64_e32 v[88:89], 0
	v_mov_b64_e32 v[90:91], 0
	v_mov_b64_e32 v[92:93], 0
	v_mov_b64_e32 v[94:95], 0
	v_mov_b64_e32 v[96:97], 0
	v_mov_b64_e32 v[98:99], 0
	v_mov_b64_e32 v[100:101], 0
	v_mov_b64_e32 v[102:103], 0
	v_mov_b64_e32 v[104:105], 0
	v_mov_b64_e32 v[106:107], 0
	v_mov_b64_e32 v[108:109], 0
	v_mov_b64_e32 v[110:111], 0
	v_mov_b64_e32 v[112:113], 0
	v_mov_b64_e32 v[114:115], 0
	v_mov_b64_e32 v[116:117], 0
	v_mov_b64_e32 v[118:119], 0
	v_mov_b64_e32 v[120:121], 0
	v_mov_b64_e32 v[122:123], 0
	v_mov_b64_e32 v[124:125], 0
	v_mov_b64_e32 v[126:127], 0

; template <class Epi, class Sched, bool ALIGN_EPI = false, bool SP2 = false>
; __device__ __forceinline__ void gemm_phase(PG8_LAS unsigned char* lds, const Gemm g, const Sched& S, const Epi& E) {
;     ...
;         const bool has_next = S.next(ui + 1, nxt);
;         const char* nA = has_next ? (const char*)g.A + (size_t)nxt.pm * tstep : cA; const char* nB = has_next ? (const char*)g.Bt + (size_t)nxt.pn * tstep : cB;
;         for (int t = 0; t < nt; t += 2) {
;             const bool last = (t == nt - 2);
;             const char* a1 = cA + (size_t)(t + 1) * kstep;
;             const char* a2 = last ? nA : cA + (size_t)(t + 2) * kstep; const char* b2 = last ? nB : cB + (size_t)(t + 2) * kstep;
;             const char* a3 = a2 + kstep; const char* b3 = b2 + kstep;
;     ...
;         for (int a = 0; a < 2; ++a)
; #pragma unroll
;             for (int b = 0; b < 2; ++b)
; #pragma unroll
;                 for (int m = 0; m < 4; ++m)
; #pragma unroll
;                     for (int n = 0; n < 2; ++n) acc[a][b][m][n] = (f32x4){0.f, 0.f, 0.f, 0.f};
;         cur = nxt; cA = nA; cB = nB; ++ui;
.LBB0_268:
	s_add_u32 s55, s26, 0x100
	v_mov_b64_e32 v[0:1], 0
	s_addc_u32 s56, s27, 0
	s_mov_b32 s57, -2
	v_mov_b64_e32 v[2:3], 0
	v_mov_b64_e32 v[4:5], 0
	v_mov_b64_e32 v[6:7], 0
	v_mov_b64_e32 v[8:9], 0
	v_mov_b64_e32 v[10:11], 0
	v_mov_b64_e32 v[12:13], 0
	v_mov_b64_e32 v[14:15], 0
	v_mov_b64_e32 v[16:17], 0
	v_mov_b64_e32 v[18:19], 0
	v_mov_b64_e32 v[20:21], 0
	v_mov_b64_e32 v[22:23], 0
	v_mov_b64_e32 v[24:25], 0
	v_mov_b64_e32 v[26:27], 0
	v_mov_b64_e32 v[28:29], 0
	v_mov_b64_e32 v[30:31], 0
	v_mov_b64_e32 v[32:33], 0
	v_mov_b64_e32 v[34:35], 0
	v_mov_b64_e32 v[36:37], 0
	v_mov_b64_e32 v[38:39], 0
	v_mov_b64_e32 v[40:41], 0
	v_mov_b64_e32 v[42:43], 0
	v_mov_b64_e32 v[44:45], 0
	v_mov_b64_e32 v[46:47], 0
	v_mov_b64_e32 v[48:49], 0
	v_mov_b64_e32 v[50:51], 0
	v_mov_b64_e32 v[52:53], 0
	v_mov_b64_e32 v[54:55], 0
	v_mov_b64_e32 v[56:57], 0
	v_mov_b64_e32 v[58:59], 0
	v_mov_b64_e32 v[60:61], 0
	v_mov_b64_e32 v[62:63], 0
	v_mov_b64_e32 v[64:65], 0
	v_mov_b64_e32 v[66:67], 0
	v_mov_b64_e32 v[68:69], 0
	v_mov_b64_e32 v[70:71], 0
	v_mov_b64_e32 v[72:73], 0
	v_mov_b64_e32 v[74:75], 0
	v_mov_b64_e32 v[76:77], 0
	v_mov_b64_e32 v[78:79], 0
	v_mov_b64_e32 v[80:81], 0
	v_mov_b64_e32 v[82:83], 0
	v_mov_b64_e32 v[84:85], 0
	v_mov_b64_e32 v[86:87], 0
	v_mov_b64_e32 v[88:89], 0
	v_mov_b64_e32 v[90:91], 0
	v_mov_b64_e32 v[92:93], 0
	v_mov_b64_e32 v[94:95], 0
	v_mov_b64_e32 v[96:97], 0
	v_mov_b64_e32 v[98:99], 0
	v_mov_b64_e32 v[100:101], 0
	v_mov_b64_e32 v[102:103], 0
	v_mov_b64_e32 v[104:105], 0
	v_mov_b64_e32 v[106:107], 0
	v_mov_b64_e32 v[108:109], 0
	v_mov_b64_e32 v[110:111], 0
	v_mov_b64_e32 v[112:113], 0
	v_mov_b64_e32 v[114:115], 0
	v_mov_b64_e32 v[116:117], 0
	v_mov_b64_e32 v[118:119], 0
	v_mov_b64_e32 v[120:121], 0
	v_mov_b64_e32 v[122:123], 0
	v_mov_b64_e32 v[124:125], 0
	v_mov_b64_e32 v[126:127], 0

; template <class Epi, class Sched, bool ALIGN_EPI = false, bool SP2 = false>
; __device__ __forceinline__ void gemm_phase(PG8_LAS unsigned char* lds, const Gemm g, const Sched& S, const Epi& E) {
;     ...
;         const bool has_next = S.next(ui + 1, nxt);
;         const char* nA = has_next ? (const char*)g.A + (size_t)nxt.pm * tstep : cA; const char* nB = has_next ? (const char*)g.Bt + (size_t)nxt.pn * tstep : cB;
;         for (int t = 0; t < nt; t += 2) {
;             const bool last = (t == nt - 2);
;             const char* a1 = cA + (size_t)(t + 1) * kstep;
;             const char* a2 = last ? nA : cA + (size_t)(t + 2) * kstep; const char* b2 = last ? nB : cB + (size_t)(t + 2) * kstep;
;             const char* a3 = a2 + kstep; const char* b3 = b2 + kstep;
;     ...
;         for (int a = 0; a < 2; ++a)
; #pragma unroll
;             for (int b = 0; b < 2; ++b)
; #pragma unroll
;                 for (int m = 0; m < 4; ++m)
; #pragma unroll
;                     for (int n = 0; n < 2; ++n) acc[a][b][m][n] = (f32x4){0.f, 0.f, 0.f, 0.f};
;         cur = nxt; cA = nA; cB = nB; ++ui;
.LBB0_342:
	s_ashr_i32 s13, s12, 31
	s_lshl_b64 s[14:15], s[12:13], 19
	s_add_u32 s14, s26, s14
	s_addc_u32 s15, s27, s15
	s_and_b64 s[16:17], s[2:3], exec
	s_cselect_b32 s13, s15, s23
	s_cselect_b32 s46, s14, s22
	s_ashr_i32 s11, s10, 31
	s_lshl_b64 s[16:17], s[10:11], 19
	s_add_u32 s16, s28, s16
	s_addc_u32 s17, s29, s17
	s_and_b64 s[24:25], s[2:3], exec
	s_cselect_b32 s11, s17, s21
	s_cselect_b32 s47, s16, s20
	s_add_u32 s48, s20, 0x100
	s_addc_u32 s49, s21, 0
	s_add_u32 s20, s22, 0x40080
	v_mov_b64_e32 v[0:1], 0
	s_addc_u32 s21, s23, 0
	s_mov_b32 s50, -2
	v_mov_b64_e32 v[2:3], 0
	v_mov_b64_e32 v[4:5], 0
	v_mov_b64_e32 v[6:7], 0
	v_mov_b64_e32 v[8:9], 0
	v_mov_b64_e32 v[10:11], 0
	v_mov_b64_e32 v[12:13], 0
	v_mov_b64_e32 v[14:15], 0
	v_mov_b64_e32 v[16:17], 0
	v_mov_b64_e32 v[18:19], 0
	v_mov_b64_e32 v[20:21], 0
	v_mov_b64_e32 v[22:23], 0
	v_mov_b64_e32 v[24:25], 0
	v_mov_b64_e32 v[26:27], 0
	v_mov_b64_e32 v[28:29], 0
	v_mov_b64_e32 v[30:31], 0
	v_mov_b64_e32 v[32:33], 0
	v_mov_b64_e32 v[34:35], 0
	v_mov_b64_e32 v[36:37], 0
	v_mov_b64_e32 v[38:39], 0
	v_mov_b64_e32 v[40:41], 0
	v_mov_b64_e32 v[42:43], 0
	v_mov_b64_e32 v[44:45], 0
	v_mov_b64_e32 v[46:47], 0
	v_mov_b64_e32 v[48:49], 0
	v_mov_b64_e32 v[50:51], 0
	v_mov_b64_e32 v[52:53], 0
	v_mov_b64_e32 v[54:55], 0
	v_mov_b64_e32 v[56:57], 0
	v_mov_b64_e32 v[58:59], 0
	v_mov_b64_e32 v[60:61], 0
	v_mov_b64_e32 v[62:63], 0
	v_mov_b64_e32 v[64:65], 0
	v_mov_b64_e32 v[66:67], 0
	v_mov_b64_e32 v[68:69], 0
	v_mov_b64_e32 v[70:71], 0
	v_mov_b64_e32 v[72:73], 0
	v_mov_b64_e32 v[74:75], 0
	v_mov_b64_e32 v[76:77], 0
	v_mov_b64_e32 v[78:79], 0
	v_mov_b64_e32 v[80:81], 0
	v_mov_b64_e32 v[82:83], 0
	v_mov_b64_e32 v[84:85], 0
	v_mov_b64_e32 v[86:87], 0
	v_mov_b64_e32 v[88:89], 0
	v_mov_b64_e32 v[90:91], 0
	v_mov_b64_e32 v[92:93], 0
	v_mov_b64_e32 v[94:95], 0
	v_mov_b64_e32 v[96:97], 0
	v_mov_b64_e32 v[98:99], 0
	v_mov_b64_e32 v[100:101], 0
	v_mov_b64_e32 v[102:103], 0
	v_mov_b64_e32 v[104:105], 0
	v_mov_b64_e32 v[106:107], 0
	v_mov_b64_e32 v[108:109], 0
	v_mov_b64_e32 v[110:111], 0
	v_mov_b64_e32 v[112:113], 0
	v_mov_b64_e32 v[114:115], 0
	v_mov_b64_e32 v[116:117], 0
	v_mov_b64_e32 v[118:119], 0
	v_mov_b64_e32 v[120:121], 0
	v_mov_b64_e32 v[122:123], 0
	v_mov_b64_e32 v[124:125], 0
	v_mov_b64_e32 v[126:127], 0

; template <class Epi, class Sched, bool ALIGN_EPI = false, bool SP2 = false>
; __device__ __forceinline__ void gemm_phase(PG8_LAS unsigned char* lds, const Gemm g, const Sched& S, const Epi& E) {
;     ...
;         const bool has_next = S.next(ui + 1, nxt);
;         const char* nA = has_next ? (const char*)g.A + (size_t)nxt.pm * tstep : cA; const char* nB = has_next ? (const char*)g.Bt + (size_t)nxt.pn * tstep : cB;
;         for (int t = 0; t < nt; t += 2) {
;             const bool last = (t == nt - 2);
;             const char* a1 = cA + (size_t)(t + 1) * kstep;
;             const char* a2 = last ? nA : cA + (size_t)(t + 2) * kstep; const char* b2 = last ? nB : cB + (size_t)(t + 2) * kstep;
;             const char* a3 = a2 + kstep; const char* b3 = b2 + kstep;
;     ...
;         for (int a = 0; a < 2; ++a)
; #pragma unroll
;             for (int b = 0; b < 2; ++b)
; #pragma unroll
;                 for (int m = 0; m < 4; ++m)
; #pragma unroll
;                     for (int n = 0; n < 2; ++n) acc[a][b][m][n] = (f32x4){0.f, 0.f, 0.f, 0.f};
;         cur = nxt; cA = nA; cB = nB; ++ui;
.LBB0_423:
	s_ashr_i32 s15, s14, 31
	s_lshl_b64 s[16:17], s[14:15], 19
	s_add_u32 s16, s0, s16
	s_addc_u32 s17, s1, s17
	s_and_b64 s[18:19], s[12:13], exec
	s_cselect_b32 s15, s17, s23
	s_cselect_b32 s44, s16, s22
	s_ashr_i32 s11, s10, 31
	s_lshl_b64 s[18:19], s[10:11], 19
	s_add_u32 s18, s26, s18
	s_addc_u32 s19, s27, s19
	s_and_b64 s[24:25], s[12:13], exec
	s_cselect_b32 s11, s19, s21
	s_cselect_b32 s45, s18, s20
	s_add_u32 s46, s20, 0x100
	s_addc_u32 s47, s21, 0
	s_add_u32 s20, s22, 0x40080
	v_mov_b64_e32 v[0:1], 0
	s_addc_u32 s21, s23, 0
	s_mov_b32 s48, -2
	v_mov_b64_e32 v[2:3], 0
	v_mov_b64_e32 v[4:5], 0
	v_mov_b64_e32 v[6:7], 0
	v_mov_b64_e32 v[8:9], 0
	v_mov_b64_e32 v[10:11], 0
	v_mov_b64_e32 v[12:13], 0
	v_mov_b64_e32 v[14:15], 0
	v_mov_b64_e32 v[16:17], 0
	v_mov_b64_e32 v[18:19], 0
	v_mov_b64_e32 v[20:21], 0
	v_mov_b64_e32 v[22:23], 0
	v_mov_b64_e32 v[24:25], 0
	v_mov_b64_e32 v[26:27], 0
	v_mov_b64_e32 v[28:29], 0
	v_mov_b64_e32 v[30:31], 0
	v_mov_b64_e32 v[32:33], 0
	v_mov_b64_e32 v[34:35], 0
	v_mov_b64_e32 v[36:37], 0
	v_mov_b64_e32 v[38:39], 0
	v_mov_b64_e32 v[40:41], 0
	v_mov_b64_e32 v[42:43], 0
	v_mov_b64_e32 v[44:45], 0
	v_mov_b64_e32 v[46:47], 0
	v_mov_b64_e32 v[48:49], 0
	v_mov_b64_e32 v[50:51], 0
	v_mov_b64_e32 v[52:53], 0
	v_mov_b64_e32 v[54:55], 0
	v_mov_b64_e32 v[56:57], 0
	v_mov_b64_e32 v[58:59], 0
	v_mov_b64_e32 v[60:61], 0
	v_mov_b64_e32 v[62:63], 0
	v_mov_b64_e32 v[64:65], 0
	v_mov_b64_e32 v[66:67], 0
	v_mov_b64_e32 v[68:69], 0
	v_mov_b64_e32 v[70:71], 0
	v_mov_b64_e32 v[72:73], 0
	v_mov_b64_e32 v[74:75], 0
	v_mov_b64_e32 v[76:77], 0
	v_mov_b64_e32 v[78:79], 0
	v_mov_b64_e32 v[80:81], 0
	v_mov_b64_e32 v[82:83], 0
	v_mov_b64_e32 v[84:85], 0
	v_mov_b64_e32 v[86:87], 0
	v_mov_b64_e32 v[88:89], 0
	v_mov_b64_e32 v[90:91], 0
	v_mov_b64_e32 v[92:93], 0
	v_mov_b64_e32 v[94:95], 0
	v_mov_b64_e32 v[96:97], 0
	v_mov_b64_e32 v[98:99], 0
	v_mov_b64_e32 v[100:101], 0
	v_mov_b64_e32 v[102:103], 0
	v_mov_b64_e32 v[104:105], 0
	v_mov_b64_e32 v[106:107], 0
	v_mov_b64_e32 v[108:109], 0
	v_mov_b64_e32 v[110:111], 0
	v_mov_b64_e32 v[112:113], 0
	v_mov_b64_e32 v[114:115], 0
	v_mov_b64_e32 v[116:117], 0
	v_mov_b64_e32 v[118:119], 0
	v_mov_b64_e32 v[120:121], 0
	v_mov_b64_e32 v[122:123], 0
	v_mov_b64_e32 v[124:125], 0
	v_mov_b64_e32 v[126:127], 0

; template <class Epi, class Sched, bool ALIGN_EPI = false, bool SP2 = false>
; __device__ __forceinline__ void gemm_phase(PG8_LAS unsigned char* lds, const Gemm g, const Sched& S, const Epi& E) {
;     ...
;         const bool has_next = S.next(ui + 1, nxt);
;         const char* nA = has_next ? (const char*)g.A + (size_t)nxt.pm * tstep : cA; const char* nB = has_next ? (const char*)g.Bt + (size_t)nxt.pn * tstep : cB;
;         for (int t = 0; t < nt; t += 2) {
;             const bool last = (t == nt - 2);
;             const char* a1 = cA + (size_t)(t + 1) * kstep;
;             const char* a2 = last ? nA : cA + (size_t)(t + 2) * kstep; const char* b2 = last ? nB : cB + (size_t)(t + 2) * kstep;
;             const char* a3 = a2 + kstep; const char* b3 = b2 + kstep;
;     ...
;         for (int a = 0; a < 2; ++a)
; #pragma unroll
;             for (int b = 0; b < 2; ++b)
; #pragma unroll
;                 for (int m = 0; m < 4; ++m)
; #pragma unroll
;                     for (int n = 0; n < 2; ++n) acc[a][b][m][n] = (f32x4){0.f, 0.f, 0.f, 0.f};
;         cur = nxt; cA = nA; cB = nB; ++ui;
.LBB0_514:
	s_add_u32 s46, s16, 0x100
	v_mov_b64_e32 v[0:1], 0
	s_addc_u32 s47, s17, 0
	s_mov_b32 s48, -2
	v_mov_b64_e32 v[2:3], 0
	v_mov_b64_e32 v[4:5], 0
	v_mov_b64_e32 v[6:7], 0
	v_mov_b64_e32 v[8:9], 0
	v_mov_b64_e32 v[10:11], 0
	v_mov_b64_e32 v[12:13], 0
	v_mov_b64_e32 v[14:15], 0
	v_mov_b64_e32 v[16:17], 0
	v_mov_b64_e32 v[18:19], 0
	v_mov_b64_e32 v[20:21], 0
	v_mov_b64_e32 v[22:23], 0
	v_mov_b64_e32 v[24:25], 0
	v_mov_b64_e32 v[26:27], 0
	v_mov_b64_e32 v[28:29], 0
	v_mov_b64_e32 v[30:31], 0
	v_mov_b64_e32 v[32:33], 0
	v_mov_b64_e32 v[34:35], 0
	v_mov_b64_e32 v[36:37], 0
	v_mov_b64_e32 v[38:39], 0
	v_mov_b64_e32 v[40:41], 0
	v_mov_b64_e32 v[42:43], 0
	v_mov_b64_e32 v[44:45], 0
	v_mov_b64_e32 v[46:47], 0
	v_mov_b64_e32 v[48:49], 0
	v_mov_b64_e32 v[50:51], 0
	v_mov_b64_e32 v[52:53], 0
	v_mov_b64_e32 v[54:55], 0
	v_mov_b64_e32 v[56:57], 0
	v_mov_b64_e32 v[58:59], 0
	v_mov_b64_e32 v[60:61], 0
	v_mov_b64_e32 v[62:63], 0
	v_mov_b64_e32 v[64:65], 0
	v_mov_b64_e32 v[66:67], 0
	v_mov_b64_e32 v[68:69], 0
	v_mov_b64_e32 v[70:71], 0
	v_mov_b64_e32 v[72:73], 0
	v_mov_b64_e32 v[74:75], 0
	v_mov_b64_e32 v[76:77], 0
	v_mov_b64_e32 v[78:79], 0
	v_mov_b64_e32 v[80:81], 0
	v_mov_b64_e32 v[82:83], 0
	v_mov_b64_e32 v[84:85], 0
	v_mov_b64_e32 v[86:87], 0
	v_mov_b64_e32 v[88:89], 0
	v_mov_b64_e32 v[90:91], 0
	v_mov_b64_e32 v[92:93], 0
	v_mov_b64_e32 v[94:95], 0
	v_mov_b64_e32 v[96:97], 0
	v_mov_b64_e32 v[98:99], 0
	v_mov_b64_e32 v[100:101], 0
	v_mov_b64_e32 v[102:103], 0
	v_mov_b64_e32 v[104:105], 0
	v_mov_b64_e32 v[106:107], 0
	v_mov_b64_e32 v[108:109], 0
	v_mov_b64_e32 v[110:111], 0
	v_mov_b64_e32 v[112:113], 0
	v_mov_b64_e32 v[114:115], 0
	v_mov_b64_e32 v[116:117], 0
	v_mov_b64_e32 v[118:119], 0
	v_mov_b64_e32 v[120:121], 0
	v_mov_b64_e32 v[122:123], 0
	v_mov_b64_e32 v[124:125], 0
	v_mov_b64_e32 v[126:127], 0

; template <class Epi, class Sched, bool ALIGN_EPI = false, bool SP2 = false>
; __device__ __forceinline__ void gemm_phase(PG8_LAS unsigned char* lds, const Gemm g, const Sched& S, const Epi& E) {
;     ...
;         const bool has_next = S.next(ui + 1, nxt);
;         const char* nA = has_next ? (const char*)g.A + (size_t)nxt.pm * tstep : cA; const char* nB = has_next ? (const char*)g.Bt + (size_t)nxt.pn * tstep : cB;
;         for (int t = 0; t < nt; t += 2) {
;             const bool last = (t == nt - 2);
;             const char* a1 = cA + (size_t)(t + 1) * kstep;
;             const char* a2 = last ? nA : cA + (size_t)(t + 2) * kstep; const char* b2 = last ? nB : cB + (size_t)(t + 2) * kstep;
;             const char* a3 = a2 + kstep; const char* b3 = b2 + kstep;
;     ...
;         for (int a = 0; a < 2; ++a)
; #pragma unroll
;             for (int b = 0; b < 2; ++b)
; #pragma unroll
;                 for (int m = 0; m < 4; ++m)
; #pragma unroll
;                     for (int n = 0; n < 2; ++n) acc[a][b][m][n] = (f32x4){0.f, 0.f, 0.f, 0.f};
;         cur = nxt; cA = nA; cB = nB; ++ui;
.LBB0_538:
	s_ashr_i32 s21, s20, 31
	s_lshl_b64 s[22:23], s[20:21], 17
	s_add_u32 s22, s48, s22
	s_addc_u32 s23, s49, s23
	s_and_b64 s[24:25], s[2:3], exec
	s_cselect_b32 s21, s23, s31
	s_cselect_b32 s68, s22, s30
	s_ashr_i32 s19, s18, 31
	s_lshl_b64 s[24:25], s[18:19], 17
	s_add_u32 s24, s50, s24
	s_addc_u32 s25, s51, s25
	s_and_b64 s[34:35], s[2:3], exec
	v_mov_b64_e32 v[0:1], 0
	s_cselect_b32 s19, s25, s29
	s_cselect_b32 s69, s24, s28
	s_mov_b32 s38, 0
	s_mov_b64 s[34:35], -1
	s_mov_b64 s[36:37], 0
	v_mov_b64_e32 v[2:3], 0
	v_mov_b64_e32 v[4:5], 0
	v_mov_b64_e32 v[6:7], 0
	v_mov_b64_e32 v[8:9], 0
	v_mov_b64_e32 v[10:11], 0
	v_mov_b64_e32 v[12:13], 0
	v_mov_b64_e32 v[14:15], 0
	v_mov_b64_e32 v[16:17], 0
	v_mov_b64_e32 v[18:19], 0
	v_mov_b64_e32 v[20:21], 0
	v_mov_b64_e32 v[22:23], 0
	v_mov_b64_e32 v[24:25], 0
	v_mov_b64_e32 v[26:27], 0
	v_mov_b64_e32 v[28:29], 0
	v_mov_b64_e32 v[30:31], 0
	v_mov_b64_e32 v[32:33], 0
	v_mov_b64_e32 v[34:35], 0
	v_mov_b64_e32 v[36:37], 0
	v_mov_b64_e32 v[38:39], 0
	v_mov_b64_e32 v[40:41], 0
	v_mov_b64_e32 v[42:43], 0
	v_mov_b64_e32 v[44:45], 0
	v_mov_b64_e32 v[46:47], 0
	v_mov_b64_e32 v[48:49], 0
	v_mov_b64_e32 v[50:51], 0
	v_mov_b64_e32 v[52:53], 0
	v_mov_b64_e32 v[54:55], 0
	v_mov_b64_e32 v[56:57], 0
	v_mov_b64_e32 v[58:59], 0
	v_mov_b64_e32 v[60:61], 0
	v_mov_b64_e32 v[62:63], 0
	v_mov_b64_e32 v[64:65], 0
	v_mov_b64_e32 v[66:67], 0
	v_mov_b64_e32 v[68:69], 0
	v_mov_b64_e32 v[70:71], 0
	v_mov_b64_e32 v[72:73], 0
	v_mov_b64_e32 v[74:75], 0
	v_mov_b64_e32 v[76:77], 0
	v_mov_b64_e32 v[78:79], 0
	v_mov_b64_e32 v[80:81], 0
	v_mov_b64_e32 v[82:83], 0
	v_mov_b64_e32 v[84:85], 0
	v_mov_b64_e32 v[86:87], 0
	v_mov_b64_e32 v[88:89], 0
	v_mov_b64_e32 v[90:91], 0
	v_mov_b64_e32 v[92:93], 0
	v_mov_b64_e32 v[94:95], 0
	v_mov_b64_e32 v[96:97], 0
	v_mov_b64_e32 v[98:99], 0
	v_mov_b64_e32 v[100:101], 0
	v_mov_b64_e32 v[102:103], 0
	v_mov_b64_e32 v[104:105], 0
	v_mov_b64_e32 v[106:107], 0
	v_mov_b64_e32 v[108:109], 0
	v_mov_b64_e32 v[110:111], 0
	v_mov_b64_e32 v[112:113], 0
	v_mov_b64_e32 v[114:115], 0
	v_mov_b64_e32 v[116:117], 0
	v_mov_b64_e32 v[118:119], 0
	v_mov_b64_e32 v[120:121], 0
	v_mov_b64_e32 v[122:123], 0
	v_mov_b64_e32 v[124:125], 0
	v_mov_b64_e32 v[126:127], 0

; template <class Epi, class Sched, bool ALIGN_EPI = false, bool SP2 = false>
; __device__ __forceinline__ void gemm_phase(PG8_LAS unsigned char* lds, const Gemm g, const Sched& S, const Epi& E) {
;     ...
;         const bool has_next = S.next(ui + 1, nxt);
;         const char* nA = has_next ? (const char*)g.A + (size_t)nxt.pm * tstep : cA; const char* nB = has_next ? (const char*)g.Bt + (size_t)nxt.pn * tstep : cB;
;         for (int t = 0; t < nt; t += 2) {
;             const bool last = (t == nt - 2);
;             const char* a1 = cA + (size_t)(t + 1) * kstep;
;             const char* a2 = last ? nA : cA + (size_t)(t + 2) * kstep; const char* b2 = last ? nB : cB + (size_t)(t + 2) * kstep;
;             const char* a3 = a2 + kstep; const char* b3 = b2 + kstep;
;     ...
;         for (int a = 0; a < 2; ++a)
; #pragma unroll
;             for (int b = 0; b < 2; ++b)
; #pragma unroll
;                 for (int m = 0; m < 4; ++m)
; #pragma unroll
;                     for (int n = 0; n < 2; ++n) acc[a][b][m][n] = (f32x4){0.f, 0.f, 0.f, 0.f};
;         cur = nxt; cA = nA; cB = nB; ++ui;
.LBB0_867:
	s_ashr_i32 s23, s22, 31
	s_lshl_b64 s[24:25], s[22:23], 19
	s_add_u32 s24, s38, s24
	s_addc_u32 s25, s39, s25
	s_and_b64 s[26:27], s[4:5], exec
	s_cselect_b32 s23, s25, s35
	s_cselect_b32 s57, s24, s34
	s_ashr_i32 s21, s20, 31
	s_lshl_b64 s[26:27], s[20:21], 19
	s_add_u32 s26, s40, s26
	s_addc_u32 s27, s41, s27
	s_and_b64 s[36:37], s[4:5], exec
	s_cselect_b32 s21, s27, s31
	s_cselect_b32 s58, s26, s30
	s_add_u32 s59, s30, 0x100
	s_addc_u32 s60, s31, 0
	s_add_u32 s30, s34, 0x40080
	v_mov_b64_e32 v[0:1], 0
	s_addc_u32 s31, s35, 0
	s_mov_b32 s61, -2
	v_mov_b64_e32 v[2:3], 0
	v_mov_b64_e32 v[4:5], 0
	v_mov_b64_e32 v[6:7], 0
	v_mov_b64_e32 v[8:9], 0
	v_mov_b64_e32 v[10:11], 0
	v_mov_b64_e32 v[12:13], 0
	v_mov_b64_e32 v[14:15], 0
	v_mov_b64_e32 v[16:17], 0
	v_mov_b64_e32 v[18:19], 0
	v_mov_b64_e32 v[20:21], 0
	v_mov_b64_e32 v[22:23], 0
	v_mov_b64_e32 v[24:25], 0
	v_mov_b64_e32 v[26:27], 0
	v_mov_b64_e32 v[28:29], 0
	v_mov_b64_e32 v[30:31], 0
	v_mov_b64_e32 v[32:33], 0
	v_mov_b64_e32 v[34:35], 0
	v_mov_b64_e32 v[36:37], 0
	v_mov_b64_e32 v[38:39], 0
	v_mov_b64_e32 v[40:41], 0
	v_mov_b64_e32 v[42:43], 0
	v_mov_b64_e32 v[44:45], 0
	v_mov_b64_e32 v[46:47], 0
	v_mov_b64_e32 v[48:49], 0
	v_mov_b64_e32 v[50:51], 0
	v_mov_b64_e32 v[52:53], 0
	v_mov_b64_e32 v[54:55], 0
	v_mov_b64_e32 v[56:57], 0
	v_mov_b64_e32 v[58:59], 0
	v_mov_b64_e32 v[60:61], 0
	v_mov_b64_e32 v[62:63], 0
	v_mov_b64_e32 v[64:65], 0
	v_mov_b64_e32 v[66:67], 0
	v_mov_b64_e32 v[68:69], 0
	v_mov_b64_e32 v[70:71], 0
	v_mov_b64_e32 v[72:73], 0
	v_mov_b64_e32 v[74:75], 0
	v_mov_b64_e32 v[76:77], 0
	v_mov_b64_e32 v[78:79], 0
	v_mov_b64_e32 v[80:81], 0
	v_mov_b64_e32 v[82:83], 0
	v_mov_b64_e32 v[84:85], 0
	v_mov_b64_e32 v[86:87], 0
	v_mov_b64_e32 v[88:89], 0
	v_mov_b64_e32 v[90:91], 0
	v_mov_b64_e32 v[92:93], 0
	v_mov_b64_e32 v[94:95], 0
	v_mov_b64_e32 v[96:97], 0
	v_mov_b64_e32 v[98:99], 0
	v_mov_b64_e32 v[100:101], 0
	v_mov_b64_e32 v[102:103], 0
	v_mov_b64_e32 v[104:105], 0
	v_mov_b64_e32 v[106:107], 0
	v_mov_b64_e32 v[108:109], 0
	v_mov_b64_e32 v[110:111], 0
	v_mov_b64_e32 v[112:113], 0
	v_mov_b64_e32 v[114:115], 0
	v_mov_b64_e32 v[116:117], 0
	v_mov_b64_e32 v[118:119], 0
	v_mov_b64_e32 v[120:121], 0
	v_mov_b64_e32 v[122:123], 0
	v_mov_b64_e32 v[124:125], 0
	v_mov_b64_e32 v[126:127], 0

; template <class Epi, class Sched, bool ALIGN_EPI = false, bool SP2 = false>
; __device__ __forceinline__ void gemm_phase(PG8_LAS unsigned char* lds, const Gemm g, const Sched& S, const Epi& E) {
;     ...
;         const bool has_next = S.next(ui + 1, nxt);
;         const char* nA = has_next ? (const char*)g.A + (size_t)nxt.pm * tstep : cA; const char* nB = has_next ? (const char*)g.Bt + (size_t)nxt.pn * tstep : cB;
;         for (int t = 0; t < nt; t += 2) {
;             const bool last = (t == nt - 2);
;             const char* a1 = cA + (size_t)(t + 1) * kstep;
;             const char* a2 = last ? nA : cA + (size_t)(t + 2) * kstep; const char* b2 = last ? nB : cB + (size_t)(t + 2) * kstep;
;             const char* a3 = a2 + kstep; const char* b3 = b2 + kstep;
;     ...
;         for (int a = 0; a < 2; ++a)
; #pragma unroll
;             for (int b = 0; b < 2; ++b)
; #pragma unroll
;                 for (int m = 0; m < 4; ++m)
; #pragma unroll
;                     for (int n = 0; n < 2; ++n) acc[a][b][m][n] = (f32x4){0.f, 0.f, 0.f, 0.f};
;         cur = nxt; cA = nA; cB = nB; ++ui;
.LBB0_936:
	s_ashr_i32 s23, s22, 31
	s_lshl_b64 s[26:27], s[22:23], 19
	s_add_u32 s26, s0, s26
	s_addc_u32 s27, s1, s27
	s_and_b64 s[28:29], s[24:25], exec
	s_cselect_b32 s23, s27, s35
	s_cselect_b32 s56, s26, s34
	s_ashr_i32 s21, s20, 31
	s_lshl_b64 s[28:29], s[20:21], 19
	s_add_u32 s28, s33, s28
	s_addc_u32 s29, s38, s29
	s_and_b64 s[36:37], s[24:25], exec
	s_cselect_b32 s21, s29, s31
	s_cselect_b32 s57, s28, s30
	s_add_u32 s58, s30, 0x100
	s_addc_u32 s59, s31, 0
	s_add_u32 s30, s34, 0x40080
	v_mov_b64_e32 v[0:1], 0
	s_addc_u32 s31, s35, 0
	s_mov_b32 s60, -2
	v_mov_b64_e32 v[2:3], 0
	v_mov_b64_e32 v[4:5], 0
	v_mov_b64_e32 v[6:7], 0
	v_mov_b64_e32 v[8:9], 0
	v_mov_b64_e32 v[10:11], 0
	v_mov_b64_e32 v[12:13], 0
	v_mov_b64_e32 v[14:15], 0
	v_mov_b64_e32 v[16:17], 0
	v_mov_b64_e32 v[18:19], 0
	v_mov_b64_e32 v[20:21], 0
	v_mov_b64_e32 v[22:23], 0
	v_mov_b64_e32 v[24:25], 0
	v_mov_b64_e32 v[26:27], 0
	v_mov_b64_e32 v[28:29], 0
	v_mov_b64_e32 v[30:31], 0
	v_mov_b64_e32 v[32:33], 0
	v_mov_b64_e32 v[34:35], 0
	v_mov_b64_e32 v[36:37], 0
	v_mov_b64_e32 v[38:39], 0
	v_mov_b64_e32 v[40:41], 0
	v_mov_b64_e32 v[42:43], 0
	v_mov_b64_e32 v[44:45], 0
	v_mov_b64_e32 v[46:47], 0
	v_mov_b64_e32 v[48:49], 0
	v_mov_b64_e32 v[50:51], 0
	v_mov_b64_e32 v[52:53], 0
	v_mov_b64_e32 v[54:55], 0
	v_mov_b64_e32 v[56:57], 0
	v_mov_b64_e32 v[58:59], 0
	v_mov_b64_e32 v[60:61], 0
	v_mov_b64_e32 v[62:63], 0
	v_mov_b64_e32 v[64:65], 0
	v_mov_b64_e32 v[66:67], 0
	v_mov_b64_e32 v[68:69], 0
	v_mov_b64_e32 v[70:71], 0
	v_mov_b64_e32 v[72:73], 0
	v_mov_b64_e32 v[74:75], 0
	v_mov_b64_e32 v[76:77], 0
	v_mov_b64_e32 v[78:79], 0
	v_mov_b64_e32 v[80:81], 0
	v_mov_b64_e32 v[82:83], 0
	v_mov_b64_e32 v[84:85], 0
	v_mov_b64_e32 v[86:87], 0
	v_mov_b64_e32 v[88:89], 0
	v_mov_b64_e32 v[90:91], 0
	v_mov_b64_e32 v[92:93], 0
	v_mov_b64_e32 v[94:95], 0
	v_mov_b64_e32 v[96:97], 0
	v_mov_b64_e32 v[98:99], 0
	v_mov_b64_e32 v[100:101], 0
	v_mov_b64_e32 v[102:103], 0
	v_mov_b64_e32 v[104:105], 0
	v_mov_b64_e32 v[106:107], 0
	v_mov_b64_e32 v[108:109], 0
	v_mov_b64_e32 v[110:111], 0
	v_mov_b64_e32 v[112:113], 0
	v_mov_b64_e32 v[114:115], 0
	v_mov_b64_e32 v[116:117], 0
	v_mov_b64_e32 v[118:119], 0
	v_mov_b64_e32 v[120:121], 0
	v_mov_b64_e32 v[122:123], 0
	v_mov_b64_e32 v[124:125], 0
	v_mov_b64_e32 v[126:127], 0

; template <class Epi, class Sched, bool ALIGN_EPI = false, bool SP2 = false>
; __device__ __forceinline__ void gemm_phase(PG8_LAS unsigned char* lds, const Gemm g, const Sched& S, const Epi& E) {
;     ...
;         const bool has_next = S.next(ui + 1, nxt);
;         const char* nA = has_next ? (const char*)g.A + (size_t)nxt.pm * tstep : cA; const char* nB = has_next ? (const char*)g.Bt + (size_t)nxt.pn * tstep : cB;
;         for (int t = 0; t < nt; t += 2) {
;             const bool last = (t == nt - 2);
;             const char* a1 = cA + (size_t)(t + 1) * kstep;
;             const char* a2 = last ? nA : cA + (size_t)(t + 2) * kstep; const char* b2 = last ? nB : cB + (size_t)(t + 2) * kstep;
;             const char* a3 = a2 + kstep; const char* b3 = b2 + kstep;
;     ...
;         for (int a = 0; a < 2; ++a)
; #pragma unroll
;             for (int b = 0; b < 2; ++b)
; #pragma unroll
;                 for (int m = 0; m < 4; ++m)
; #pragma unroll
;                     for (int n = 0; n < 2; ++n) acc[a][b][m][n] = (f32x4){0.f, 0.f, 0.f, 0.f};
;         cur = nxt; cA = nA; cB = nB; ++ui;
.LBB0_1016:
	s_ashr_i32 s15, s14, 31
	s_lshl_b64 s[16:17], s[14:15], 19
	s_add_u32 s16, s29, s16
	s_addc_u32 s17, s30, s17
	s_and_b64 s[18:19], s[4:5], exec
	s_cselect_b32 s15, s17, s25
	s_cselect_b32 s46, s16, s24
	s_ashr_i32 s13, s12, 31
	s_lshl_b64 s[18:19], s[12:13], 19
	s_add_u32 s18, s31, s18
	s_addc_u32 s19, s33, s19
	s_and_b64 s[26:27], s[4:5], exec
	s_cselect_b32 s13, s19, s23
	s_cselect_b32 s47, s18, s22
	s_add_u32 s48, s22, 0x100
	s_addc_u32 s49, s23, 0
	s_add_u32 s22, s24, 0x40080
	v_mov_b64_e32 v[0:1], 0
	s_addc_u32 s23, s25, 0
	s_mov_b32 s50, -2
	v_mov_b64_e32 v[2:3], 0
	v_mov_b64_e32 v[4:5], 0
	v_mov_b64_e32 v[6:7], 0
	v_mov_b64_e32 v[8:9], 0
	v_mov_b64_e32 v[10:11], 0
	v_mov_b64_e32 v[12:13], 0
	v_mov_b64_e32 v[14:15], 0
	v_mov_b64_e32 v[16:17], 0
	v_mov_b64_e32 v[18:19], 0
	v_mov_b64_e32 v[20:21], 0
	v_mov_b64_e32 v[22:23], 0
	v_mov_b64_e32 v[24:25], 0
	v_mov_b64_e32 v[26:27], 0
	v_mov_b64_e32 v[28:29], 0
	v_mov_b64_e32 v[30:31], 0
	v_mov_b64_e32 v[32:33], 0
	v_mov_b64_e32 v[34:35], 0
	v_mov_b64_e32 v[36:37], 0
	v_mov_b64_e32 v[38:39], 0
	v_mov_b64_e32 v[40:41], 0
	v_mov_b64_e32 v[42:43], 0
	v_mov_b64_e32 v[44:45], 0
	v_mov_b64_e32 v[46:47], 0
	v_mov_b64_e32 v[48:49], 0
	v_mov_b64_e32 v[50:51], 0
	v_mov_b64_e32 v[52:53], 0
	v_mov_b64_e32 v[54:55], 0
	v_mov_b64_e32 v[56:57], 0
	v_mov_b64_e32 v[58:59], 0
	v_mov_b64_e32 v[60:61], 0
	v_mov_b64_e32 v[62:63], 0
	v_mov_b64_e32 v[64:65], 0
	v_mov_b64_e32 v[66:67], 0
	v_mov_b64_e32 v[68:69], 0
	v_mov_b64_e32 v[70:71], 0
	v_mov_b64_e32 v[72:73], 0
	v_mov_b64_e32 v[74:75], 0
	v_mov_b64_e32 v[76:77], 0
	v_mov_b64_e32 v[78:79], 0
	v_mov_b64_e32 v[80:81], 0
	v_mov_b64_e32 v[82:83], 0
	v_mov_b64_e32 v[84:85], 0
	v_mov_b64_e32 v[86:87], 0
	v_mov_b64_e32 v[88:89], 0
	v_mov_b64_e32 v[90:91], 0
	v_mov_b64_e32 v[92:93], 0
	v_mov_b64_e32 v[94:95], 0
	v_mov_b64_e32 v[96:97], 0
	v_mov_b64_e32 v[98:99], 0
	v_mov_b64_e32 v[100:101], 0
	v_mov_b64_e32 v[102:103], 0
	v_mov_b64_e32 v[104:105], 0
	v_mov_b64_e32 v[106:107], 0
	v_mov_b64_e32 v[108:109], 0
	v_mov_b64_e32 v[110:111], 0
	v_mov_b64_e32 v[112:113], 0
	v_mov_b64_e32 v[114:115], 0
	v_mov_b64_e32 v[116:117], 0
	v_mov_b64_e32 v[118:119], 0
	v_mov_b64_e32 v[120:121], 0
	v_mov_b64_e32 v[122:123], 0
	v_mov_b64_e32 v[124:125], 0
	v_mov_b64_e32 v[126:127], 0

; template <class Epi, class Sched, bool ALIGN_EPI = false, bool SP2 = false>
; __device__ __forceinline__ void gemm_phase(PG8_LAS unsigned char* lds, const Gemm g, const Sched& S, const Epi& E) {
;     ...
;         const bool has_next = S.next(ui + 1, nxt);
;         const char* nA = has_next ? (const char*)g.A + (size_t)nxt.pm * tstep : cA; const char* nB = has_next ? (const char*)g.Bt + (size_t)nxt.pn * tstep : cB;
;         for (int t = 0; t < nt; t += 2) {
;             const bool last = (t == nt - 2);
;             const char* a1 = cA + (size_t)(t + 1) * kstep;
;             const char* a2 = last ? nA : cA + (size_t)(t + 2) * kstep; const char* b2 = last ? nB : cB + (size_t)(t + 2) * kstep;
;             const char* a3 = a2 + kstep; const char* b3 = b2 + kstep;
;     ...
;         for (int a = 0; a < 2; ++a)
; #pragma unroll
;             for (int b = 0; b < 2; ++b)
; #pragma unroll
;                 for (int m = 0; m < 4; ++m)
; #pragma unroll
;                     for (int n = 0; n < 2; ++n) acc[a][b][m][n] = (f32x4){0.f, 0.f, 0.f, 0.f};
;         cur = nxt; cA = nA; cB = nB; ++ui;
.LBB0_1088:
	s_add_u32 s55, s24, 0x100
	v_mov_b64_e32 v[0:1], 0
	s_addc_u32 s56, s25, 0
	s_mov_b32 s57, -2
	v_mov_b64_e32 v[2:3], 0
	v_mov_b64_e32 v[4:5], 0
	v_mov_b64_e32 v[6:7], 0
	v_mov_b64_e32 v[8:9], 0
	v_mov_b64_e32 v[10:11], 0
	v_mov_b64_e32 v[12:13], 0
	v_mov_b64_e32 v[14:15], 0
	v_mov_b64_e32 v[16:17], 0
	v_mov_b64_e32 v[18:19], 0
	v_mov_b64_e32 v[20:21], 0
	v_mov_b64_e32 v[22:23], 0
	v_mov_b64_e32 v[24:25], 0
	v_mov_b64_e32 v[26:27], 0
	v_mov_b64_e32 v[28:29], 0
	v_mov_b64_e32 v[30:31], 0
	v_mov_b64_e32 v[32:33], 0
	v_mov_b64_e32 v[34:35], 0
	v_mov_b64_e32 v[36:37], 0
	v_mov_b64_e32 v[38:39], 0
	v_mov_b64_e32 v[40:41], 0
	v_mov_b64_e32 v[42:43], 0
	v_mov_b64_e32 v[44:45], 0
	v_mov_b64_e32 v[46:47], 0
	v_mov_b64_e32 v[48:49], 0
	v_mov_b64_e32 v[50:51], 0
	v_mov_b64_e32 v[52:53], 0
	v_mov_b64_e32 v[54:55], 0
	v_mov_b64_e32 v[56:57], 0
	v_mov_b64_e32 v[58:59], 0
	v_mov_b64_e32 v[60:61], 0
	v_mov_b64_e32 v[62:63], 0
	v_mov_b64_e32 v[64:65], 0
	v_mov_b64_e32 v[66:67], 0
	v_mov_b64_e32 v[68:69], 0
	v_mov_b64_e32 v[70:71], 0
	v_mov_b64_e32 v[72:73], 0
	v_mov_b64_e32 v[74:75], 0
	v_mov_b64_e32 v[76:77], 0
	v_mov_b64_e32 v[78:79], 0
	v_mov_b64_e32 v[80:81], 0
	v_mov_b64_e32 v[82:83], 0
	v_mov_b64_e32 v[84:85], 0
	v_mov_b64_e32 v[86:87], 0
	v_mov_b64_e32 v[88:89], 0
	v_mov_b64_e32 v[90:91], 0
	v_mov_b64_e32 v[92:93], 0
	v_mov_b64_e32 v[94:95], 0
	v_mov_b64_e32 v[96:97], 0
	v_mov_b64_e32 v[98:99], 0
	v_mov_b64_e32 v[100:101], 0
	v_mov_b64_e32 v[102:103], 0
	v_mov_b64_e32 v[104:105], 0
	v_mov_b64_e32 v[106:107], 0
	v_mov_b64_e32 v[108:109], 0
	v_mov_b64_e32 v[110:111], 0
	v_mov_b64_e32 v[112:113], 0
	v_mov_b64_e32 v[114:115], 0
	v_mov_b64_e32 v[116:117], 0
	v_mov_b64_e32 v[118:119], 0
	v_mov_b64_e32 v[120:121], 0
	v_mov_b64_e32 v[122:123], 0
	v_mov_b64_e32 v[124:125], 0
	v_mov_b64_e32 v[126:127], 0

; template <class Epi, class Sched, bool ALIGN_EPI = false, bool SP2 = false>
; __device__ __forceinline__ void gemm_phase(PG8_LAS unsigned char* lds, const Gemm g, const Sched& S, const Epi& E) {
;     ...
;         const bool has_next = S.next(ui + 1, nxt);
;         const char* nA = has_next ? (const char*)g.A + (size_t)nxt.pm * tstep : cA; const char* nB = has_next ? (const char*)g.Bt + (size_t)nxt.pn * tstep : cB;
;         for (int t = 0; t < nt; t += 2) {
;             const bool last = (t == nt - 2);
;             const char* a1 = cA + (size_t)(t + 1) * kstep;
;             const char* a2 = last ? nA : cA + (size_t)(t + 2) * kstep; const char* b2 = last ? nB : cB + (size_t)(t + 2) * kstep;
;             const char* a3 = a2 + kstep; const char* b3 = b2 + kstep;
;     ...
;         for (int a = 0; a < 2; ++a)
; #pragma unroll
;             for (int b = 0; b < 2; ++b)
; #pragma unroll
;                 for (int m = 0; m < 4; ++m)
; #pragma unroll
;                     for (int n = 0; n < 2; ++n) acc[a][b][m][n] = (f32x4){0.f, 0.f, 0.f, 0.f};
;         cur = nxt; cA = nA; cB = nB; ++ui;
.LBB0_1157:
	s_add_u32 s53, s26, 0x100
	v_mov_b64_e32 v[0:1], 0
	s_addc_u32 s54, s27, 0
	s_mov_b32 s55, -2
	v_mov_b64_e32 v[2:3], 0
	v_mov_b64_e32 v[4:5], 0
	v_mov_b64_e32 v[6:7], 0
	v_mov_b64_e32 v[8:9], 0
	v_mov_b64_e32 v[10:11], 0
	v_mov_b64_e32 v[12:13], 0
	v_mov_b64_e32 v[14:15], 0
	v_mov_b64_e32 v[16:17], 0
	v_mov_b64_e32 v[18:19], 0
	v_mov_b64_e32 v[20:21], 0
	v_mov_b64_e32 v[22:23], 0
	v_mov_b64_e32 v[24:25], 0
	v_mov_b64_e32 v[26:27], 0
	v_mov_b64_e32 v[28:29], 0
	v_mov_b64_e32 v[30:31], 0
	v_mov_b64_e32 v[32:33], 0
	v_mov_b64_e32 v[34:35], 0
	v_mov_b64_e32 v[36:37], 0
	v_mov_b64_e32 v[38:39], 0
	v_mov_b64_e32 v[40:41], 0
	v_mov_b64_e32 v[42:43], 0
	v_mov_b64_e32 v[44:45], 0
	v_mov_b64_e32 v[46:47], 0
	v_mov_b64_e32 v[48:49], 0
	v_mov_b64_e32 v[50:51], 0
	v_mov_b64_e32 v[52:53], 0
	v_mov_b64_e32 v[54:55], 0
	v_mov_b64_e32 v[56:57], 0
	v_mov_b64_e32 v[58:59], 0
	v_mov_b64_e32 v[60:61], 0
	v_mov_b64_e32 v[62:63], 0
	v_mov_b64_e32 v[64:65], 0
	v_mov_b64_e32 v[66:67], 0
	v_mov_b64_e32 v[68:69], 0
	v_mov_b64_e32 v[70:71], 0
	v_mov_b64_e32 v[72:73], 0
	v_mov_b64_e32 v[74:75], 0
	v_mov_b64_e32 v[76:77], 0
	v_mov_b64_e32 v[78:79], 0
	v_mov_b64_e32 v[80:81], 0
	v_mov_b64_e32 v[82:83], 0
	v_mov_b64_e32 v[84:85], 0
	v_mov_b64_e32 v[86:87], 0
	v_mov_b64_e32 v[88:89], 0
	v_mov_b64_e32 v[90:91], 0
	v_mov_b64_e32 v[92:93], 0
	v_mov_b64_e32 v[94:95], 0
	v_mov_b64_e32 v[96:97], 0
	v_mov_b64_e32 v[98:99], 0
	v_mov_b64_e32 v[100:101], 0
	v_mov_b64_e32 v[102:103], 0
	v_mov_b64_e32 v[104:105], 0
	v_mov_b64_e32 v[106:107], 0
	v_mov_b64_e32 v[108:109], 0
	v_mov_b64_e32 v[110:111], 0
	v_mov_b64_e32 v[112:113], 0
	v_mov_b64_e32 v[114:115], 0
	v_mov_b64_e32 v[116:117], 0
	v_mov_b64_e32 v[118:119], 0
	v_mov_b64_e32 v[120:121], 0
	v_mov_b64_e32 v[122:123], 0
	v_mov_b64_e32 v[124:125], 0
	v_mov_b64_e32 v[126:127], 0
